# sample-row pool GEMM halves split across the rb=0 and rb=1 workgroups of each group
# baseline (speedup 1.0000x reference)
.LBB0_557:
	v_mov_b64_e32 v[34:35], s[28:29]
	v_lshl_or_b32 v104, s8, 8, v140
	v_mad_i64_i32 v[34:35], s[10:11], v32, s18, v[34:35]
	v_ashrrev_i32_e32 v105, 31, v104
	v_lshl_add_u64 v[106:107], v[34:35], 0, s[4:5]
	v_lshlrev_b64 v[34:35], 1, v[104:105]
	v_or_b32_e32 v108, 16, v104
	v_lshl_add_u64 v[36:37], v[106:107], 0, v[34:35]
	v_ashrrev_i32_e32 v109, 31, v108
	v_or_b32_e32 v110, 32, v104
	v_or_b32_e32 v112, 48, v104
	s_waitcnt lgkmcnt(0)
	s_barrier
	v_mov_b32_e32 v170, v36
	v_mov_b32_e32 v171, v37
	v_lshlrev_b64 v[132:133], 12, v[32:33]
	v_lshl_add_u64 v[130:131], v[104:105], 2, s[60:61]
	v_lshl_add_u64 v[132:133], s[30:31], 0, v[132:133]
	v_mov_b32_e32 v64, v143
	v_add_u32_e32 v103, 0x10800, v143
	v_lshl_add_u64 v[132:133], v[104:105], 1, v[132:133]
	ds_read_b128 v[174:177], v64
	ds_read_b128 v[178:181], v64 offset:64
	ds_read_b128 v[182:185], v64 offset:128
	ds_read_b128 v[186:189], v64 offset:192
	ds_read_b128 v[190:193], v64 offset:256
	ds_read_b128 v[194:197], v64 offset:320
	ds_read_b128 v[198:201], v64 offset:384
	ds_read_b128 v[202:205], v64 offset:448
	global_load_dwordx2 v[32:33], v[170:171], off
	global_load_dwordx2 v[34:35], v[170:171], off offset:32
	global_load_dwordx2 v[36:37], v[170:171], off offset:64
	global_load_dwordx2 v[38:39], v[170:171], off offset:96
	global_load_dwordx2 v[40:41], v[170:171], off offset:128
	global_load_dwordx2 v[42:43], v[170:171], off offset:160
	global_load_dwordx2 v[44:45], v[170:171], off offset:192
	global_load_dwordx2 v[46:47], v[170:171], off offset:224
	global_load_dwordx2 v[48:49], v[170:171], off offset:256
	global_load_dwordx2 v[50:51], v[170:171], off offset:288
	global_load_dwordx2 v[52:53], v[170:171], off offset:320
	global_load_dwordx2 v[54:55], v[170:171], off offset:352
	global_load_dwordx2 v[56:57], v[170:171], off offset:384
	global_load_dwordx2 v[58:59], v[170:171], off offset:416
	global_load_dwordx2 v[60:61], v[170:171], off offset:448
	global_load_dwordx2 v[62:63], v[170:171], off offset:480
	global_load_dwordx4 v[118:121], v[130:131], off
	global_load_dwordx4 v[122:125], v[130:131], off offset:64
	global_load_dwordx4 v[126:129], v[130:131], off offset:128
	s_waitcnt lgkmcnt(0)
	ds_read_b128 v[206:209], v64 offset:8448
	ds_read_b128 v[210:213], v64 offset:8512
	ds_read_b128 v[214:217], v64 offset:8576
	ds_read_b128 v[218:221], v64 offset:8640
	ds_read_b128 v[222:225], v64 offset:8704
	ds_read_b128 v[226:229], v64 offset:8768
	ds_read_b128 v[230:233], v64 offset:8832
	ds_read_b128 v[234:237], v64 offset:8896
	s_waitcnt vmcnt(26)
	v_mfma_f32_16x16x32_bf16 v[162:165], v[174:177], v[0:3], 0
	s_waitcnt vmcnt(25)
	v_mfma_f32_16x16x32_bf16 v[162:165], v[178:181], v[4:7], v[162:165]
	s_waitcnt vmcnt(24)
	v_mfma_f32_16x16x32_bf16 v[162:165], v[182:185], v[8:11], v[162:165]
	s_waitcnt vmcnt(23)
	v_mfma_f32_16x16x32_bf16 v[162:165], v[186:189], v[12:15], v[162:165]
	s_waitcnt vmcnt(22)
	v_mfma_f32_16x16x32_bf16 v[162:165], v[190:193], v[16:19], v[162:165]
	s_waitcnt vmcnt(21)
	v_mfma_f32_16x16x32_bf16 v[162:165], v[194:197], v[20:23], v[162:165]
	s_waitcnt vmcnt(20)
	v_mfma_f32_16x16x32_bf16 v[162:165], v[198:201], v[24:27], v[162:165]
	s_waitcnt vmcnt(19)
	v_mfma_f32_16x16x32_bf16 v[162:165], v[202:205], v[28:31], v[162:165]
	s_waitcnt vmcnt(18)
	v_lshlrev_b32_e32 v170, 16, v32
	v_and_b32_e32 v171, 0xffff0000, v32
	v_mul_f32_e32 v166, 0xbfb8aa3b, v170
	v_exp_f32_e32 v166, v166
	s_nop 0
	v_add_f32_e32 v166, 1.0, v166
	v_rcp_f32_e32 v172, v166
	v_mul_f32_e32 v166, 0xbfb8aa3b, v171
	v_exp_f32_e32 v166, v166
	s_nop 0
	v_add_f32_e32 v166, 1.0, v166
	v_rcp_f32_e32 v173, v166
	s_waitcnt vmcnt(2)
	v_pk_mul_f32 v[118:119], v[118:119], v[162:163]
	v_pk_mul_f32 v[120:121], v[120:121], v[164:165]
	v_pk_mul_f32 v[172:173], v[172:173], v[170:171]
	s_nop 0
	v_pk_mul_f32 v[118:119], v[172:173], v[118:119]
	s_nop 0
	v_cvt_pk_bf16_f32 v166, v118, v119
	v_lshlrev_b32_e32 v170, 16, v33
	v_and_b32_e32 v171, 0xffff0000, v33
	v_mul_f32_e32 v167, 0xbfb8aa3b, v170
	v_exp_f32_e32 v167, v167
	s_nop 0
	v_add_f32_e32 v167, 1.0, v167
	v_rcp_f32_e32 v172, v167
	v_mul_f32_e32 v167, 0xbfb8aa3b, v171
	v_exp_f32_e32 v167, v167
	s_nop 0
	v_add_f32_e32 v167, 1.0, v167
	v_rcp_f32_e32 v173, v167
	s_nop 1
	v_pk_mul_f32 v[172:173], v[172:173], v[170:171]
	s_nop 0
	v_pk_mul_f32 v[120:121], v[172:173], v[120:121]
	s_nop 0
	v_cvt_pk_bf16_f32 v167, v120, v121
	s_nop 0
	global_store_dwordx2 v[132:133], v[166:167], off offset:2048
	global_load_dwordx4 v[118:121], v[130:131], off offset:192
	s_waitcnt lgkmcnt(0)
	ds_read_b128 v[174:177], v64 offset:16896
	ds_read_b128 v[178:181], v64 offset:16960
	ds_read_b128 v[182:185], v64 offset:17024
	ds_read_b128 v[186:189], v64 offset:17088
	ds_read_b128 v[190:193], v64 offset:17152
	ds_read_b128 v[194:197], v64 offset:17216
	ds_read_b128 v[198:201], v64 offset:17280
	ds_read_b128 v[202:205], v64 offset:17344
	v_mfma_f32_16x16x32_bf16 v[162:165], v[206:209], v[0:3], 0
	v_mfma_f32_16x16x32_bf16 v[162:165], v[210:213], v[4:7], v[162:165]
	v_mfma_f32_16x16x32_bf16 v[162:165], v[214:217], v[8:11], v[162:165]
	v_mfma_f32_16x16x32_bf16 v[162:165], v[218:221], v[12:15], v[162:165]
	v_mfma_f32_16x16x32_bf16 v[162:165], v[222:225], v[16:19], v[162:165]
	v_mfma_f32_16x16x32_bf16 v[162:165], v[226:229], v[20:23], v[162:165]
	v_mfma_f32_16x16x32_bf16 v[162:165], v[230:233], v[24:27], v[162:165]
	v_mfma_f32_16x16x32_bf16 v[162:165], v[234:237], v[28:31], v[162:165]
	s_waitcnt vmcnt(19)
	v_lshlrev_b32_e32 v170, 16, v34
	v_and_b32_e32 v171, 0xffff0000, v34
	v_mul_f32_e32 v166, 0xbfb8aa3b, v170
	v_exp_f32_e32 v166, v166
	s_nop 0
	v_add_f32_e32 v166, 1.0, v166
	v_rcp_f32_e32 v172, v166
	v_mul_f32_e32 v166, 0xbfb8aa3b, v171
	v_exp_f32_e32 v166, v166
	s_nop 0
	v_add_f32_e32 v166, 1.0, v166
	v_rcp_f32_e32 v173, v166
	s_waitcnt vmcnt(3)
	v_pk_mul_f32 v[122:123], v[122:123], v[162:163]
	v_pk_mul_f32 v[124:125], v[124:125], v[164:165]
	v_pk_mul_f32 v[172:173], v[172:173], v[170:171]
	s_nop 0
	v_pk_mul_f32 v[122:123], v[172:173], v[122:123]
	s_nop 0
	v_cvt_pk_bf16_f32 v166, v122, v123
	v_lshlrev_b32_e32 v170, 16, v35
	v_and_b32_e32 v171, 0xffff0000, v35
	v_mul_f32_e32 v167, 0xbfb8aa3b, v170
	v_exp_f32_e32 v167, v167
	s_nop 0
	v_add_f32_e32 v167, 1.0, v167
	v_rcp_f32_e32 v172, v167
	v_mul_f32_e32 v167, 0xbfb8aa3b, v171
	v_exp_f32_e32 v167, v167
	s_nop 0
	v_add_f32_e32 v167, 1.0, v167
	v_rcp_f32_e32 v173, v167
	s_nop 1
	v_pk_mul_f32 v[172:173], v[172:173], v[170:171]
	s_nop 0
	v_pk_mul_f32 v[124:125], v[172:173], v[124:125]
	s_nop 0
	v_cvt_pk_bf16_f32 v167, v124, v125
	s_nop 0
	global_store_dwordx2 v[132:133], v[166:167], off offset:2080
	global_load_dwordx4 v[122:125], v[130:131], off offset:256
	s_waitcnt lgkmcnt(0)
	ds_read_b128 v[206:209], v64 offset:25344
	ds_read_b128 v[210:213], v64 offset:25408
	ds_read_b128 v[214:217], v64 offset:25472
	ds_read_b128 v[218:221], v64 offset:25536
	ds_read_b128 v[222:225], v64 offset:25600
	ds_read_b128 v[226:229], v64 offset:25664
	ds_read_b128 v[230:233], v64 offset:25728
	ds_read_b128 v[234:237], v64 offset:25792
	v_mfma_f32_16x16x32_bf16 v[162:165], v[174:177], v[0:3], 0
	v_mfma_f32_16x16x32_bf16 v[162:165], v[178:181], v[4:7], v[162:165]
	v_mfma_f32_16x16x32_bf16 v[162:165], v[182:185], v[8:11], v[162:165]
	v_mfma_f32_16x16x32_bf16 v[162:165], v[186:189], v[12:15], v[162:165]
	v_mfma_f32_16x16x32_bf16 v[162:165], v[190:193], v[16:19], v[162:165]
	v_mfma_f32_16x16x32_bf16 v[162:165], v[194:197], v[20:23], v[162:165]
	v_mfma_f32_16x16x32_bf16 v[162:165], v[198:201], v[24:27], v[162:165]
	v_mfma_f32_16x16x32_bf16 v[162:165], v[202:205], v[28:31], v[162:165]
	s_waitcnt vmcnt(20)
	v_lshlrev_b32_e32 v170, 16, v36
	v_and_b32_e32 v171, 0xffff0000, v36
	v_mul_f32_e32 v166, 0xbfb8aa3b, v170
	v_exp_f32_e32 v166, v166
	s_nop 0
	v_add_f32_e32 v166, 1.0, v166
	v_rcp_f32_e32 v172, v166
	v_mul_f32_e32 v166, 0xbfb8aa3b, v171
	v_exp_f32_e32 v166, v166
	s_nop 0
	v_add_f32_e32 v166, 1.0, v166
	v_rcp_f32_e32 v173, v166
	s_waitcnt vmcnt(4)
	v_pk_mul_f32 v[126:127], v[126:127], v[162:163]
	v_pk_mul_f32 v[128:129], v[128:129], v[164:165]
	v_pk_mul_f32 v[172:173], v[172:173], v[170:171]
	s_nop 0
	v_pk_mul_f32 v[126:127], v[172:173], v[126:127]
	s_nop 0
	v_cvt_pk_bf16_f32 v166, v126, v127
	v_lshlrev_b32_e32 v170, 16, v37
	v_and_b32_e32 v171, 0xffff0000, v37
	v_mul_f32_e32 v167, 0xbfb8aa3b, v170
	v_exp_f32_e32 v167, v167
	s_nop 0
	v_add_f32_e32 v167, 1.0, v167
	v_rcp_f32_e32 v172, v167
	v_mul_f32_e32 v167, 0xbfb8aa3b, v171
	v_exp_f32_e32 v167, v167
	s_nop 0
	v_add_f32_e32 v167, 1.0, v167
	v_rcp_f32_e32 v173, v167
	s_nop 1
	v_pk_mul_f32 v[172:173], v[172:173], v[170:171]
	s_nop 0
	v_pk_mul_f32 v[128:129], v[172:173], v[128:129]
	s_nop 0
	v_cvt_pk_bf16_f32 v167, v128, v129
	s_nop 0
	global_store_dwordx2 v[132:133], v[166:167], off offset:2112
	global_load_dwordx4 v[126:129], v[130:131], off offset:320
	s_waitcnt lgkmcnt(0)
	ds_read_b128 v[174:177], v64 offset:33792
	ds_read_b128 v[178:181], v64 offset:33856
	ds_read_b128 v[182:185], v64 offset:33920
	ds_read_b128 v[186:189], v64 offset:33984
	ds_read_b128 v[190:193], v64 offset:34048
	ds_read_b128 v[194:197], v64 offset:34112
	ds_read_b128 v[198:201], v64 offset:34176
	ds_read_b128 v[202:205], v64 offset:34240
	v_mfma_f32_16x16x32_bf16 v[162:165], v[206:209], v[0:3], 0
	v_mfma_f32_16x16x32_bf16 v[162:165], v[210:213], v[4:7], v[162:165]
	v_mfma_f32_16x16x32_bf16 v[162:165], v[214:217], v[8:11], v[162:165]
	v_mfma_f32_16x16x32_bf16 v[162:165], v[218:221], v[12:15], v[162:165]
	v_mfma_f32_16x16x32_bf16 v[162:165], v[222:225], v[16:19], v[162:165]
	v_mfma_f32_16x16x32_bf16 v[162:165], v[226:229], v[20:23], v[162:165]
	v_mfma_f32_16x16x32_bf16 v[162:165], v[230:233], v[24:27], v[162:165]
	v_mfma_f32_16x16x32_bf16 v[162:165], v[234:237], v[28:31], v[162:165]
	s_waitcnt vmcnt(21)
	v_lshlrev_b32_e32 v170, 16, v38
	v_and_b32_e32 v171, 0xffff0000, v38
	v_mul_f32_e32 v166, 0xbfb8aa3b, v170
	v_exp_f32_e32 v166, v166
	s_nop 0
	v_add_f32_e32 v166, 1.0, v166
	v_rcp_f32_e32 v172, v166
	v_mul_f32_e32 v166, 0xbfb8aa3b, v171
	v_exp_f32_e32 v166, v166
	s_nop 0
	v_add_f32_e32 v166, 1.0, v166
	v_rcp_f32_e32 v173, v166
	s_waitcnt vmcnt(4)
	v_pk_mul_f32 v[118:119], v[118:119], v[162:163]
	v_pk_mul_f32 v[120:121], v[120:121], v[164:165]
	v_pk_mul_f32 v[172:173], v[172:173], v[170:171]
	s_nop 0
	v_pk_mul_f32 v[118:119], v[172:173], v[118:119]
	s_nop 0
	v_cvt_pk_bf16_f32 v166, v118, v119
	v_lshlrev_b32_e32 v170, 16, v39
	v_and_b32_e32 v171, 0xffff0000, v39
	v_mul_f32_e32 v167, 0xbfb8aa3b, v170
	v_exp_f32_e32 v167, v167
	s_nop 0
	v_add_f32_e32 v167, 1.0, v167
	v_rcp_f32_e32 v172, v167
	v_mul_f32_e32 v167, 0xbfb8aa3b, v171
	v_exp_f32_e32 v167, v167
	s_nop 0
	v_add_f32_e32 v167, 1.0, v167
	v_rcp_f32_e32 v173, v167
	s_nop 1
	v_pk_mul_f32 v[172:173], v[172:173], v[170:171]
	s_nop 0
	v_pk_mul_f32 v[120:121], v[172:173], v[120:121]
	s_nop 0
	v_cvt_pk_bf16_f32 v167, v120, v121
	s_nop 0
	global_store_dwordx2 v[132:133], v[166:167], off offset:2144
	global_load_dwordx4 v[118:121], v[130:131], off offset:384
	s_waitcnt lgkmcnt(0)
	ds_read_b128 v[206:209], v64 offset:42240
	ds_read_b128 v[210:213], v64 offset:42304
	ds_read_b128 v[214:217], v64 offset:42368
	ds_read_b128 v[218:221], v64 offset:42432
	ds_read_b128 v[222:225], v64 offset:42496
	ds_read_b128 v[226:229], v64 offset:42560
	ds_read_b128 v[230:233], v64 offset:42624
	ds_read_b128 v[234:237], v64 offset:42688
	v_mfma_f32_16x16x32_bf16 v[162:165], v[174:177], v[0:3], 0
	v_mfma_f32_16x16x32_bf16 v[162:165], v[178:181], v[4:7], v[162:165]
	v_mfma_f32_16x16x32_bf16 v[162:165], v[182:185], v[8:11], v[162:165]
	v_mfma_f32_16x16x32_bf16 v[162:165], v[186:189], v[12:15], v[162:165]
	v_mfma_f32_16x16x32_bf16 v[162:165], v[190:193], v[16:19], v[162:165]
	v_mfma_f32_16x16x32_bf16 v[162:165], v[194:197], v[20:23], v[162:165]
	v_mfma_f32_16x16x32_bf16 v[162:165], v[198:201], v[24:27], v[162:165]
	v_mfma_f32_16x16x32_bf16 v[162:165], v[202:205], v[28:31], v[162:165]
	s_waitcnt vmcnt(22)
	v_lshlrev_b32_e32 v170, 16, v40
	v_and_b32_e32 v171, 0xffff0000, v40
	v_mul_f32_e32 v166, 0xbfb8aa3b, v170
	v_exp_f32_e32 v166, v166
	s_nop 0
	v_add_f32_e32 v166, 1.0, v166
	v_rcp_f32_e32 v172, v166
	v_mul_f32_e32 v166, 0xbfb8aa3b, v171
	v_exp_f32_e32 v166, v166
	s_nop 0
	v_add_f32_e32 v166, 1.0, v166
	v_rcp_f32_e32 v173, v166
	s_waitcnt vmcnt(4)
	v_pk_mul_f32 v[122:123], v[122:123], v[162:163]
	v_pk_mul_f32 v[124:125], v[124:125], v[164:165]
	v_pk_mul_f32 v[172:173], v[172:173], v[170:171]
	s_nop 0
	v_pk_mul_f32 v[122:123], v[172:173], v[122:123]
	s_nop 0
	v_cvt_pk_bf16_f32 v166, v122, v123
	v_lshlrev_b32_e32 v170, 16, v41
	v_and_b32_e32 v171, 0xffff0000, v41
	v_mul_f32_e32 v167, 0xbfb8aa3b, v170
	v_exp_f32_e32 v167, v167
	s_nop 0
	v_add_f32_e32 v167, 1.0, v167
	v_rcp_f32_e32 v172, v167
	v_mul_f32_e32 v167, 0xbfb8aa3b, v171
	v_exp_f32_e32 v167, v167
	s_nop 0
	v_add_f32_e32 v167, 1.0, v167
	v_rcp_f32_e32 v173, v167
	s_nop 1
	v_pk_mul_f32 v[172:173], v[172:173], v[170:171]
	s_nop 0
	v_pk_mul_f32 v[124:125], v[172:173], v[124:125]
	s_nop 0
	v_cvt_pk_bf16_f32 v167, v124, v125
	s_nop 0
	global_store_dwordx2 v[132:133], v[166:167], off offset:2176
	global_load_dwordx4 v[122:125], v[130:131], off offset:448
	s_waitcnt lgkmcnt(0)
	ds_read_b128 v[174:177], v64 offset:50688
	ds_read_b128 v[178:181], v64 offset:50752
	ds_read_b128 v[182:185], v64 offset:50816
	ds_read_b128 v[186:189], v64 offset:50880
	ds_read_b128 v[190:193], v64 offset:50944
	ds_read_b128 v[194:197], v64 offset:51008
	ds_read_b128 v[198:201], v64 offset:51072
	ds_read_b128 v[202:205], v64 offset:51136
	v_mfma_f32_16x16x32_bf16 v[162:165], v[206:209], v[0:3], 0
	v_mfma_f32_16x16x32_bf16 v[162:165], v[210:213], v[4:7], v[162:165]
	v_mfma_f32_16x16x32_bf16 v[162:165], v[214:217], v[8:11], v[162:165]
	v_mfma_f32_16x16x32_bf16 v[162:165], v[218:221], v[12:15], v[162:165]
	v_mfma_f32_16x16x32_bf16 v[162:165], v[222:225], v[16:19], v[162:165]
	v_mfma_f32_16x16x32_bf16 v[162:165], v[226:229], v[20:23], v[162:165]
	v_mfma_f32_16x16x32_bf16 v[162:165], v[230:233], v[24:27], v[162:165]
	v_mfma_f32_16x16x32_bf16 v[162:165], v[234:237], v[28:31], v[162:165]
	s_waitcnt vmcnt(23)
	v_lshlrev_b32_e32 v170, 16, v42
	v_and_b32_e32 v171, 0xffff0000, v42
	v_mul_f32_e32 v166, 0xbfb8aa3b, v170
	v_exp_f32_e32 v166, v166
	s_nop 0
	v_add_f32_e32 v166, 1.0, v166
	v_rcp_f32_e32 v172, v166
	v_mul_f32_e32 v166, 0xbfb8aa3b, v171
	v_exp_f32_e32 v166, v166
	s_nop 0
	v_add_f32_e32 v166, 1.0, v166
	v_rcp_f32_e32 v173, v166
	s_waitcnt vmcnt(4)
	v_pk_mul_f32 v[126:127], v[126:127], v[162:163]
	v_pk_mul_f32 v[128:129], v[128:129], v[164:165]
	v_pk_mul_f32 v[172:173], v[172:173], v[170:171]
	s_nop 0
	v_pk_mul_f32 v[126:127], v[172:173], v[126:127]
	s_nop 0
	v_cvt_pk_bf16_f32 v166, v126, v127
	v_lshlrev_b32_e32 v170, 16, v43
	v_and_b32_e32 v171, 0xffff0000, v43
	v_mul_f32_e32 v167, 0xbfb8aa3b, v170
	v_exp_f32_e32 v167, v167
	s_nop 0
	v_add_f32_e32 v167, 1.0, v167
	v_rcp_f32_e32 v172, v167
	v_mul_f32_e32 v167, 0xbfb8aa3b, v171
	v_exp_f32_e32 v167, v167
	s_nop 0
	v_add_f32_e32 v167, 1.0, v167
	v_rcp_f32_e32 v173, v167
	s_nop 1
	v_pk_mul_f32 v[172:173], v[172:173], v[170:171]
	s_nop 0
	v_pk_mul_f32 v[128:129], v[172:173], v[128:129]
	s_nop 0
	v_cvt_pk_bf16_f32 v167, v128, v129
	s_nop 0
	global_store_dwordx2 v[132:133], v[166:167], off offset:2208
	global_load_dwordx4 v[126:129], v[130:131], off offset:512
	s_waitcnt lgkmcnt(0)
	ds_read_b128 v[206:209], v64 offset:59136
	ds_read_b128 v[210:213], v64 offset:59200
	ds_read_b128 v[214:217], v64 offset:59264
	ds_read_b128 v[218:221], v64 offset:59328
	ds_read_b128 v[222:225], v64 offset:59392
	ds_read_b128 v[226:229], v64 offset:59456
	ds_read_b128 v[230:233], v64 offset:59520
	ds_read_b128 v[234:237], v64 offset:59584
	v_mfma_f32_16x16x32_bf16 v[162:165], v[174:177], v[0:3], 0
	v_mfma_f32_16x16x32_bf16 v[162:165], v[178:181], v[4:7], v[162:165]
	v_mfma_f32_16x16x32_bf16 v[162:165], v[182:185], v[8:11], v[162:165]
	v_mfma_f32_16x16x32_bf16 v[162:165], v[186:189], v[12:15], v[162:165]
	v_mfma_f32_16x16x32_bf16 v[162:165], v[190:193], v[16:19], v[162:165]
	v_mfma_f32_16x16x32_bf16 v[162:165], v[194:197], v[20:23], v[162:165]
	v_mfma_f32_16x16x32_bf16 v[162:165], v[198:201], v[24:27], v[162:165]
	v_mfma_f32_16x16x32_bf16 v[162:165], v[202:205], v[28:31], v[162:165]
	s_waitcnt vmcnt(24)
	v_lshlrev_b32_e32 v170, 16, v44
	v_and_b32_e32 v171, 0xffff0000, v44
	v_mul_f32_e32 v166, 0xbfb8aa3b, v170
	v_exp_f32_e32 v166, v166
	s_nop 0
	v_add_f32_e32 v166, 1.0, v166
	v_rcp_f32_e32 v172, v166
	v_mul_f32_e32 v166, 0xbfb8aa3b, v171
	v_exp_f32_e32 v166, v166
	s_nop 0
	v_add_f32_e32 v166, 1.0, v166
	v_rcp_f32_e32 v173, v166
	s_waitcnt vmcnt(4)
	v_pk_mul_f32 v[118:119], v[118:119], v[162:163]
	v_pk_mul_f32 v[120:121], v[120:121], v[164:165]
	v_pk_mul_f32 v[172:173], v[172:173], v[170:171]
	s_nop 0
	v_pk_mul_f32 v[118:119], v[172:173], v[118:119]
	s_nop 0
	v_cvt_pk_bf16_f32 v166, v118, v119
	v_lshlrev_b32_e32 v170, 16, v45
	v_and_b32_e32 v171, 0xffff0000, v45
	v_mul_f32_e32 v167, 0xbfb8aa3b, v170
	v_exp_f32_e32 v167, v167
	s_nop 0
	v_add_f32_e32 v167, 1.0, v167
	v_rcp_f32_e32 v172, v167
	v_mul_f32_e32 v167, 0xbfb8aa3b, v171
	v_exp_f32_e32 v167, v167
	s_nop 0
	v_add_f32_e32 v167, 1.0, v167
	v_rcp_f32_e32 v173, v167
	s_nop 1
	v_pk_mul_f32 v[172:173], v[172:173], v[170:171]
	s_nop 0
	v_pk_mul_f32 v[120:121], v[172:173], v[120:121]
	s_nop 0
	v_cvt_pk_bf16_f32 v167, v120, v121
	s_nop 0
	global_store_dwordx2 v[132:133], v[166:167], off offset:2240
	global_load_dwordx4 v[118:121], v[130:131], off offset:576
	s_waitcnt lgkmcnt(0)
	ds_read_b128 v[174:177], v103
	ds_read_b128 v[178:181], v103 offset:64
	ds_read_b128 v[182:185], v103 offset:128
	ds_read_b128 v[186:189], v103 offset:192
	ds_read_b128 v[190:193], v103 offset:256
	ds_read_b128 v[194:197], v103 offset:320
	ds_read_b128 v[198:201], v103 offset:384
	ds_read_b128 v[202:205], v103 offset:448
	v_mfma_f32_16x16x32_bf16 v[162:165], v[206:209], v[0:3], 0
	v_mfma_f32_16x16x32_bf16 v[162:165], v[210:213], v[4:7], v[162:165]
	v_mfma_f32_16x16x32_bf16 v[162:165], v[214:217], v[8:11], v[162:165]
	v_mfma_f32_16x16x32_bf16 v[162:165], v[218:221], v[12:15], v[162:165]
	v_mfma_f32_16x16x32_bf16 v[162:165], v[222:225], v[16:19], v[162:165]
	v_mfma_f32_16x16x32_bf16 v[162:165], v[226:229], v[20:23], v[162:165]
	v_mfma_f32_16x16x32_bf16 v[162:165], v[230:233], v[24:27], v[162:165]
	v_mfma_f32_16x16x32_bf16 v[162:165], v[234:237], v[28:31], v[162:165]
	s_waitcnt vmcnt(25)
	v_lshlrev_b32_e32 v170, 16, v46
	v_and_b32_e32 v171, 0xffff0000, v46
	v_mul_f32_e32 v166, 0xbfb8aa3b, v170
	v_exp_f32_e32 v166, v166
	s_nop 0
	v_add_f32_e32 v166, 1.0, v166
	v_rcp_f32_e32 v172, v166
	v_mul_f32_e32 v166, 0xbfb8aa3b, v171
	v_exp_f32_e32 v166, v166
	s_nop 0
	v_add_f32_e32 v166, 1.0, v166
	v_rcp_f32_e32 v173, v166
	s_waitcnt vmcnt(4)
	v_pk_mul_f32 v[122:123], v[122:123], v[162:163]
	v_pk_mul_f32 v[124:125], v[124:125], v[164:165]
	v_pk_mul_f32 v[172:173], v[172:173], v[170:171]
	s_nop 0
	v_pk_mul_f32 v[122:123], v[172:173], v[122:123]
	s_nop 0
	v_cvt_pk_bf16_f32 v166, v122, v123
	v_lshlrev_b32_e32 v170, 16, v47
	v_and_b32_e32 v171, 0xffff0000, v47
	v_mul_f32_e32 v167, 0xbfb8aa3b, v170
	v_exp_f32_e32 v167, v167
	s_nop 0
	v_add_f32_e32 v167, 1.0, v167
	v_rcp_f32_e32 v172, v167
	v_mul_f32_e32 v167, 0xbfb8aa3b, v171
	v_exp_f32_e32 v167, v167
	s_nop 0
	v_add_f32_e32 v167, 1.0, v167
	v_rcp_f32_e32 v173, v167
	s_nop 1
	v_pk_mul_f32 v[172:173], v[172:173], v[170:171]
	s_nop 0
	v_pk_mul_f32 v[124:125], v[172:173], v[124:125]
	s_nop 0
	v_cvt_pk_bf16_f32 v167, v124, v125
	s_nop 0
	global_store_dwordx2 v[132:133], v[166:167], off offset:2272
	global_load_dwordx4 v[122:125], v[130:131], off offset:640
	s_waitcnt lgkmcnt(0)
	ds_read_b128 v[206:209], v103 offset:8448
	ds_read_b128 v[210:213], v103 offset:8512
	ds_read_b128 v[214:217], v103 offset:8576
	ds_read_b128 v[218:221], v103 offset:8640
	ds_read_b128 v[222:225], v103 offset:8704
	ds_read_b128 v[226:229], v103 offset:8768
	ds_read_b128 v[230:233], v103 offset:8832
	ds_read_b128 v[234:237], v103 offset:8896
	v_mfma_f32_16x16x32_bf16 v[162:165], v[174:177], v[0:3], 0
	v_mfma_f32_16x16x32_bf16 v[162:165], v[178:181], v[4:7], v[162:165]
	v_mfma_f32_16x16x32_bf16 v[162:165], v[182:185], v[8:11], v[162:165]
	v_mfma_f32_16x16x32_bf16 v[162:165], v[186:189], v[12:15], v[162:165]
	v_mfma_f32_16x16x32_bf16 v[162:165], v[190:193], v[16:19], v[162:165]
	v_mfma_f32_16x16x32_bf16 v[162:165], v[194:197], v[20:23], v[162:165]
	v_mfma_f32_16x16x32_bf16 v[162:165], v[198:201], v[24:27], v[162:165]
	v_mfma_f32_16x16x32_bf16 v[162:165], v[202:205], v[28:31], v[162:165]
	s_waitcnt vmcnt(26)
	v_lshlrev_b32_e32 v170, 16, v48
	v_and_b32_e32 v171, 0xffff0000, v48
	v_mul_f32_e32 v166, 0xbfb8aa3b, v170
	v_exp_f32_e32 v166, v166
	s_nop 0
	v_add_f32_e32 v166, 1.0, v166
	v_rcp_f32_e32 v172, v166
	v_mul_f32_e32 v166, 0xbfb8aa3b, v171
	v_exp_f32_e32 v166, v166
	s_nop 0
	v_add_f32_e32 v166, 1.0, v166
	v_rcp_f32_e32 v173, v166
	s_waitcnt vmcnt(4)
	v_pk_mul_f32 v[126:127], v[126:127], v[162:163]
	v_pk_mul_f32 v[128:129], v[128:129], v[164:165]
	v_pk_mul_f32 v[172:173], v[172:173], v[170:171]
	s_nop 0
	v_pk_mul_f32 v[126:127], v[172:173], v[126:127]
	s_nop 0
	v_cvt_pk_bf16_f32 v166, v126, v127
	v_lshlrev_b32_e32 v170, 16, v49
	v_and_b32_e32 v171, 0xffff0000, v49
	v_mul_f32_e32 v167, 0xbfb8aa3b, v170
	v_exp_f32_e32 v167, v167
	s_nop 0
	v_add_f32_e32 v167, 1.0, v167
	v_rcp_f32_e32 v172, v167
	v_mul_f32_e32 v167, 0xbfb8aa3b, v171
	v_exp_f32_e32 v167, v167
	s_nop 0
	v_add_f32_e32 v167, 1.0, v167
	v_rcp_f32_e32 v173, v167
	s_nop 1
	v_pk_mul_f32 v[172:173], v[172:173], v[170:171]
	s_nop 0
	v_pk_mul_f32 v[128:129], v[172:173], v[128:129]
	s_nop 0
	v_cvt_pk_bf16_f32 v167, v128, v129
	s_nop 0
	global_store_dwordx2 v[132:133], v[166:167], off offset:2304
	global_load_dwordx4 v[126:129], v[130:131], off offset:704
	s_waitcnt lgkmcnt(0)
	ds_read_b128 v[174:177], v103 offset:16896
	ds_read_b128 v[178:181], v103 offset:16960
	ds_read_b128 v[182:185], v103 offset:17024
	ds_read_b128 v[186:189], v103 offset:17088
	ds_read_b128 v[190:193], v103 offset:17152
	ds_read_b128 v[194:197], v103 offset:17216
	ds_read_b128 v[198:201], v103 offset:17280
	ds_read_b128 v[202:205], v103 offset:17344
	v_mfma_f32_16x16x32_bf16 v[162:165], v[206:209], v[0:3], 0
	v_mfma_f32_16x16x32_bf16 v[162:165], v[210:213], v[4:7], v[162:165]
	v_mfma_f32_16x16x32_bf16 v[162:165], v[214:217], v[8:11], v[162:165]
	v_mfma_f32_16x16x32_bf16 v[162:165], v[218:221], v[12:15], v[162:165]
	v_mfma_f32_16x16x32_bf16 v[162:165], v[222:225], v[16:19], v[162:165]
	v_mfma_f32_16x16x32_bf16 v[162:165], v[226:229], v[20:23], v[162:165]
	v_mfma_f32_16x16x32_bf16 v[162:165], v[230:233], v[24:27], v[162:165]
	v_mfma_f32_16x16x32_bf16 v[162:165], v[234:237], v[28:31], v[162:165]
	s_waitcnt vmcnt(27)
	v_lshlrev_b32_e32 v170, 16, v50
	v_and_b32_e32 v171, 0xffff0000, v50
	v_mul_f32_e32 v166, 0xbfb8aa3b, v170
	v_exp_f32_e32 v166, v166
	s_nop 0
	v_add_f32_e32 v166, 1.0, v166
	v_rcp_f32_e32 v172, v166
	v_mul_f32_e32 v166, 0xbfb8aa3b, v171
	v_exp_f32_e32 v166, v166
	s_nop 0
	v_add_f32_e32 v166, 1.0, v166
	v_rcp_f32_e32 v173, v166
	s_waitcnt vmcnt(4)
	v_pk_mul_f32 v[118:119], v[118:119], v[162:163]
	v_pk_mul_f32 v[120:121], v[120:121], v[164:165]
	v_pk_mul_f32 v[172:173], v[172:173], v[170:171]
	s_nop 0
	v_pk_mul_f32 v[118:119], v[172:173], v[118:119]
	s_nop 0
	v_cvt_pk_bf16_f32 v166, v118, v119
	v_lshlrev_b32_e32 v170, 16, v51
	v_and_b32_e32 v171, 0xffff0000, v51
	v_mul_f32_e32 v167, 0xbfb8aa3b, v170
	v_exp_f32_e32 v167, v167
	s_nop 0
	v_add_f32_e32 v167, 1.0, v167
	v_rcp_f32_e32 v172, v167
	v_mul_f32_e32 v167, 0xbfb8aa3b, v171
	v_exp_f32_e32 v167, v167
	s_nop 0
	v_add_f32_e32 v167, 1.0, v167
	v_rcp_f32_e32 v173, v167
	s_nop 1
	v_pk_mul_f32 v[172:173], v[172:173], v[170:171]
	s_nop 0
	v_pk_mul_f32 v[120:121], v[172:173], v[120:121]
	s_nop 0
	v_cvt_pk_bf16_f32 v167, v120, v121
	s_nop 0
	global_store_dwordx2 v[132:133], v[166:167], off offset:2336
	global_load_dwordx4 v[118:121], v[130:131], off offset:768
	s_waitcnt lgkmcnt(0)
	ds_read_b128 v[206:209], v103 offset:25344
	ds_read_b128 v[210:213], v103 offset:25408
	ds_read_b128 v[214:217], v103 offset:25472
	ds_read_b128 v[218:221], v103 offset:25536
	ds_read_b128 v[222:225], v103 offset:25600
	ds_read_b128 v[226:229], v103 offset:25664
	ds_read_b128 v[230:233], v103 offset:25728
	ds_read_b128 v[234:237], v103 offset:25792
	v_mfma_f32_16x16x32_bf16 v[162:165], v[174:177], v[0:3], 0
	v_mfma_f32_16x16x32_bf16 v[162:165], v[178:181], v[4:7], v[162:165]
	v_mfma_f32_16x16x32_bf16 v[162:165], v[182:185], v[8:11], v[162:165]
	v_mfma_f32_16x16x32_bf16 v[162:165], v[186:189], v[12:15], v[162:165]
	v_mfma_f32_16x16x32_bf16 v[162:165], v[190:193], v[16:19], v[162:165]
	v_mfma_f32_16x16x32_bf16 v[162:165], v[194:197], v[20:23], v[162:165]
	v_mfma_f32_16x16x32_bf16 v[162:165], v[198:201], v[24:27], v[162:165]
	v_mfma_f32_16x16x32_bf16 v[162:165], v[202:205], v[28:31], v[162:165]
	s_waitcnt vmcnt(28)
	v_lshlrev_b32_e32 v170, 16, v52
	v_and_b32_e32 v171, 0xffff0000, v52
	v_mul_f32_e32 v166, 0xbfb8aa3b, v170
	v_exp_f32_e32 v166, v166
	s_nop 0
	v_add_f32_e32 v166, 1.0, v166
	v_rcp_f32_e32 v172, v166
	v_mul_f32_e32 v166, 0xbfb8aa3b, v171
	v_exp_f32_e32 v166, v166
	s_nop 0
	v_add_f32_e32 v166, 1.0, v166
	v_rcp_f32_e32 v173, v166
	s_waitcnt vmcnt(4)
	v_pk_mul_f32 v[122:123], v[122:123], v[162:163]
	v_pk_mul_f32 v[124:125], v[124:125], v[164:165]
	v_pk_mul_f32 v[172:173], v[172:173], v[170:171]
	s_nop 0
	v_pk_mul_f32 v[122:123], v[172:173], v[122:123]
	s_nop 0
	v_cvt_pk_bf16_f32 v166, v122, v123
	v_lshlrev_b32_e32 v170, 16, v53
	v_and_b32_e32 v171, 0xffff0000, v53
	v_mul_f32_e32 v167, 0xbfb8aa3b, v170
	v_exp_f32_e32 v167, v167
	s_nop 0
	v_add_f32_e32 v167, 1.0, v167
	v_rcp_f32_e32 v172, v167
	v_mul_f32_e32 v167, 0xbfb8aa3b, v171
	v_exp_f32_e32 v167, v167
	s_nop 0
	v_add_f32_e32 v167, 1.0, v167
	v_rcp_f32_e32 v173, v167
	s_nop 1
	v_pk_mul_f32 v[172:173], v[172:173], v[170:171]
	s_nop 0
	v_pk_mul_f32 v[124:125], v[172:173], v[124:125]
	s_nop 0
	v_cvt_pk_bf16_f32 v167, v124, v125
	s_nop 0
	global_store_dwordx2 v[132:133], v[166:167], off offset:2368
	global_load_dwordx4 v[122:125], v[130:131], off offset:832
	s_waitcnt lgkmcnt(0)
	ds_read_b128 v[174:177], v103 offset:33792
	ds_read_b128 v[178:181], v103 offset:33856
	ds_read_b128 v[182:185], v103 offset:33920
	ds_read_b128 v[186:189], v103 offset:33984
	ds_read_b128 v[190:193], v103 offset:34048
	ds_read_b128 v[194:197], v103 offset:34112
	ds_read_b128 v[198:201], v103 offset:34176
	ds_read_b128 v[202:205], v103 offset:34240
	v_mfma_f32_16x16x32_bf16 v[162:165], v[206:209], v[0:3], 0
	v_mfma_f32_16x16x32_bf16 v[162:165], v[210:213], v[4:7], v[162:165]
	v_mfma_f32_16x16x32_bf16 v[162:165], v[214:217], v[8:11], v[162:165]
	v_mfma_f32_16x16x32_bf16 v[162:165], v[218:221], v[12:15], v[162:165]
	v_mfma_f32_16x16x32_bf16 v[162:165], v[222:225], v[16:19], v[162:165]
	v_mfma_f32_16x16x32_bf16 v[162:165], v[226:229], v[20:23], v[162:165]
	v_mfma_f32_16x16x32_bf16 v[162:165], v[230:233], v[24:27], v[162:165]
	v_mfma_f32_16x16x32_bf16 v[162:165], v[234:237], v[28:31], v[162:165]
	s_waitcnt vmcnt(29)
	v_lshlrev_b32_e32 v170, 16, v54
	v_and_b32_e32 v171, 0xffff0000, v54
	v_mul_f32_e32 v166, 0xbfb8aa3b, v170
	v_exp_f32_e32 v166, v166
	s_nop 0
	v_add_f32_e32 v166, 1.0, v166
	v_rcp_f32_e32 v172, v166
	v_mul_f32_e32 v166, 0xbfb8aa3b, v171
	v_exp_f32_e32 v166, v166
	s_nop 0
	v_add_f32_e32 v166, 1.0, v166
	v_rcp_f32_e32 v173, v166
	s_waitcnt vmcnt(4)
	v_pk_mul_f32 v[126:127], v[126:127], v[162:163]
	v_pk_mul_f32 v[128:129], v[128:129], v[164:165]
	v_pk_mul_f32 v[172:173], v[172:173], v[170:171]
	s_nop 0
	v_pk_mul_f32 v[126:127], v[172:173], v[126:127]
	s_nop 0
	v_cvt_pk_bf16_f32 v166, v126, v127
	v_lshlrev_b32_e32 v170, 16, v55
	v_and_b32_e32 v171, 0xffff0000, v55
	v_mul_f32_e32 v167, 0xbfb8aa3b, v170
	v_exp_f32_e32 v167, v167
	s_nop 0
	v_add_f32_e32 v167, 1.0, v167
	v_rcp_f32_e32 v172, v167
	v_mul_f32_e32 v167, 0xbfb8aa3b, v171
	v_exp_f32_e32 v167, v167
	s_nop 0
	v_add_f32_e32 v167, 1.0, v167
	v_rcp_f32_e32 v173, v167
	s_nop 1
	v_pk_mul_f32 v[172:173], v[172:173], v[170:171]
	s_nop 0
	v_pk_mul_f32 v[128:129], v[172:173], v[128:129]
	s_nop 0
	v_cvt_pk_bf16_f32 v167, v128, v129
	s_nop 0
	global_store_dwordx2 v[132:133], v[166:167], off offset:2400
	global_load_dwordx4 v[126:129], v[130:131], off offset:896
	s_waitcnt lgkmcnt(0)
	ds_read_b128 v[206:209], v103 offset:42240
	ds_read_b128 v[210:213], v103 offset:42304
	ds_read_b128 v[214:217], v103 offset:42368
	ds_read_b128 v[218:221], v103 offset:42432
	ds_read_b128 v[222:225], v103 offset:42496
	ds_read_b128 v[226:229], v103 offset:42560
	ds_read_b128 v[230:233], v103 offset:42624
	ds_read_b128 v[234:237], v103 offset:42688
	v_mfma_f32_16x16x32_bf16 v[162:165], v[174:177], v[0:3], 0
	v_mfma_f32_16x16x32_bf16 v[162:165], v[178:181], v[4:7], v[162:165]
	v_mfma_f32_16x16x32_bf16 v[162:165], v[182:185], v[8:11], v[162:165]
	v_mfma_f32_16x16x32_bf16 v[162:165], v[186:189], v[12:15], v[162:165]
	v_mfma_f32_16x16x32_bf16 v[162:165], v[190:193], v[16:19], v[162:165]
	v_mfma_f32_16x16x32_bf16 v[162:165], v[194:197], v[20:23], v[162:165]
	v_mfma_f32_16x16x32_bf16 v[162:165], v[198:201], v[24:27], v[162:165]
	v_mfma_f32_16x16x32_bf16 v[162:165], v[202:205], v[28:31], v[162:165]
	s_waitcnt vmcnt(30)
	v_lshlrev_b32_e32 v170, 16, v56
	v_and_b32_e32 v171, 0xffff0000, v56
	v_mul_f32_e32 v166, 0xbfb8aa3b, v170
	v_exp_f32_e32 v166, v166
	s_nop 0
	v_add_f32_e32 v166, 1.0, v166
	v_rcp_f32_e32 v172, v166
	v_mul_f32_e32 v166, 0xbfb8aa3b, v171
	v_exp_f32_e32 v166, v166
	s_nop 0
	v_add_f32_e32 v166, 1.0, v166
	v_rcp_f32_e32 v173, v166
	s_waitcnt vmcnt(4)
	v_pk_mul_f32 v[118:119], v[118:119], v[162:163]
	v_pk_mul_f32 v[120:121], v[120:121], v[164:165]
	v_pk_mul_f32 v[172:173], v[172:173], v[170:171]
	s_nop 0
	v_pk_mul_f32 v[118:119], v[172:173], v[118:119]
	s_nop 0
	v_cvt_pk_bf16_f32 v166, v118, v119
	v_lshlrev_b32_e32 v170, 16, v57
	v_and_b32_e32 v171, 0xffff0000, v57
	v_mul_f32_e32 v167, 0xbfb8aa3b, v170
	v_exp_f32_e32 v167, v167
	s_nop 0
	v_add_f32_e32 v167, 1.0, v167
	v_rcp_f32_e32 v172, v167
	v_mul_f32_e32 v167, 0xbfb8aa3b, v171
	v_exp_f32_e32 v167, v167
	s_nop 0
	v_add_f32_e32 v167, 1.0, v167
	v_rcp_f32_e32 v173, v167
	s_nop 1
	v_pk_mul_f32 v[172:173], v[172:173], v[170:171]
	s_nop 0
	v_pk_mul_f32 v[120:121], v[172:173], v[120:121]
	s_nop 0
	v_cvt_pk_bf16_f32 v167, v120, v121
	s_nop 0
	global_store_dwordx2 v[132:133], v[166:167], off offset:2432
	global_load_dwordx4 v[118:121], v[130:131], off offset:960
	s_waitcnt lgkmcnt(0)
	ds_read_b128 v[174:177], v103 offset:50688
	ds_read_b128 v[178:181], v103 offset:50752
	ds_read_b128 v[182:185], v103 offset:50816
	ds_read_b128 v[186:189], v103 offset:50880
	ds_read_b128 v[190:193], v103 offset:50944
	ds_read_b128 v[194:197], v103 offset:51008
	ds_read_b128 v[198:201], v103 offset:51072
	ds_read_b128 v[202:205], v103 offset:51136
	v_mfma_f32_16x16x32_bf16 v[162:165], v[206:209], v[0:3], 0
	v_mfma_f32_16x16x32_bf16 v[162:165], v[210:213], v[4:7], v[162:165]
	v_mfma_f32_16x16x32_bf16 v[162:165], v[214:217], v[8:11], v[162:165]
	v_mfma_f32_16x16x32_bf16 v[162:165], v[218:221], v[12:15], v[162:165]
	v_mfma_f32_16x16x32_bf16 v[162:165], v[222:225], v[16:19], v[162:165]
	v_mfma_f32_16x16x32_bf16 v[162:165], v[226:229], v[20:23], v[162:165]
	v_mfma_f32_16x16x32_bf16 v[162:165], v[230:233], v[24:27], v[162:165]
	v_mfma_f32_16x16x32_bf16 v[162:165], v[234:237], v[28:31], v[162:165]
	s_waitcnt vmcnt(31)
	v_lshlrev_b32_e32 v170, 16, v58
	v_and_b32_e32 v171, 0xffff0000, v58
	v_mul_f32_e32 v166, 0xbfb8aa3b, v170
	v_exp_f32_e32 v166, v166
	s_nop 0
	v_add_f32_e32 v166, 1.0, v166
	v_rcp_f32_e32 v172, v166
	v_mul_f32_e32 v166, 0xbfb8aa3b, v171
	v_exp_f32_e32 v166, v166
	s_nop 0
	v_add_f32_e32 v166, 1.0, v166
	v_rcp_f32_e32 v173, v166
	s_waitcnt vmcnt(4)
	v_pk_mul_f32 v[122:123], v[122:123], v[162:163]
	v_pk_mul_f32 v[124:125], v[124:125], v[164:165]
	v_pk_mul_f32 v[172:173], v[172:173], v[170:171]
	s_nop 0
	v_pk_mul_f32 v[122:123], v[172:173], v[122:123]
	s_nop 0
	v_cvt_pk_bf16_f32 v166, v122, v123
	v_lshlrev_b32_e32 v170, 16, v59
	v_and_b32_e32 v171, 0xffff0000, v59
	v_mul_f32_e32 v167, 0xbfb8aa3b, v170
	v_exp_f32_e32 v167, v167
	s_nop 0
	v_add_f32_e32 v167, 1.0, v167
	v_rcp_f32_e32 v172, v167
	v_mul_f32_e32 v167, 0xbfb8aa3b, v171
	v_exp_f32_e32 v167, v167
	s_nop 0
	v_add_f32_e32 v167, 1.0, v167
	v_rcp_f32_e32 v173, v167
	s_nop 1
	v_pk_mul_f32 v[172:173], v[172:173], v[170:171]
	s_nop 0
	v_pk_mul_f32 v[124:125], v[172:173], v[124:125]
	s_nop 0
	v_cvt_pk_bf16_f32 v167, v124, v125
	s_nop 0
	global_store_dwordx2 v[132:133], v[166:167], off offset:2464
	s_waitcnt lgkmcnt(0)
	ds_read_b128 v[206:209], v103 offset:59136
	ds_read_b128 v[210:213], v103 offset:59200
	ds_read_b128 v[214:217], v103 offset:59264
	ds_read_b128 v[218:221], v103 offset:59328
	ds_read_b128 v[222:225], v103 offset:59392
	ds_read_b128 v[226:229], v103 offset:59456
	ds_read_b128 v[230:233], v103 offset:59520
	ds_read_b128 v[234:237], v103 offset:59584
	v_mfma_f32_16x16x32_bf16 v[162:165], v[174:177], v[0:3], 0
	v_mfma_f32_16x16x32_bf16 v[162:165], v[178:181], v[4:7], v[162:165]
	v_mfma_f32_16x16x32_bf16 v[162:165], v[182:185], v[8:11], v[162:165]
	v_mfma_f32_16x16x32_bf16 v[162:165], v[186:189], v[12:15], v[162:165]
	v_mfma_f32_16x16x32_bf16 v[162:165], v[190:193], v[16:19], v[162:165]
	v_mfma_f32_16x16x32_bf16 v[162:165], v[194:197], v[20:23], v[162:165]
	v_mfma_f32_16x16x32_bf16 v[162:165], v[198:201], v[24:27], v[162:165]
	v_mfma_f32_16x16x32_bf16 v[162:165], v[202:205], v[28:31], v[162:165]
	s_waitcnt vmcnt(31)
	v_lshlrev_b32_e32 v170, 16, v60
	v_and_b32_e32 v171, 0xffff0000, v60
	v_mul_f32_e32 v166, 0xbfb8aa3b, v170
	v_exp_f32_e32 v166, v166
	s_nop 0
	v_add_f32_e32 v166, 1.0, v166
	v_rcp_f32_e32 v172, v166
	v_mul_f32_e32 v166, 0xbfb8aa3b, v171
	v_exp_f32_e32 v166, v166
	s_nop 0
	v_add_f32_e32 v166, 1.0, v166
	v_rcp_f32_e32 v173, v166
	s_waitcnt vmcnt(3)
	v_pk_mul_f32 v[126:127], v[126:127], v[162:163]
	v_pk_mul_f32 v[128:129], v[128:129], v[164:165]
	v_pk_mul_f32 v[172:173], v[172:173], v[170:171]
	s_nop 0
	v_pk_mul_f32 v[126:127], v[172:173], v[126:127]
	s_nop 0
	v_cvt_pk_bf16_f32 v166, v126, v127
	v_lshlrev_b32_e32 v170, 16, v61
	v_and_b32_e32 v171, 0xffff0000, v61
	v_mul_f32_e32 v167, 0xbfb8aa3b, v170
	v_exp_f32_e32 v167, v167
	s_nop 0
	v_add_f32_e32 v167, 1.0, v167
	v_rcp_f32_e32 v172, v167
	v_mul_f32_e32 v167, 0xbfb8aa3b, v171
	v_exp_f32_e32 v167, v167
	s_nop 0
	v_add_f32_e32 v167, 1.0, v167
	v_rcp_f32_e32 v173, v167
	s_nop 1
	v_pk_mul_f32 v[172:173], v[172:173], v[170:171]
	s_nop 0
	v_pk_mul_f32 v[128:129], v[172:173], v[128:129]
	s_nop 0
	v_cvt_pk_bf16_f32 v167, v128, v129
	s_nop 0
	global_store_dwordx2 v[132:133], v[166:167], off offset:2496
	s_waitcnt lgkmcnt(0)
	v_mfma_f32_16x16x32_bf16 v[162:165], v[206:209], v[0:3], 0
	v_mfma_f32_16x16x32_bf16 v[162:165], v[210:213], v[4:7], v[162:165]
	v_mfma_f32_16x16x32_bf16 v[162:165], v[214:217], v[8:11], v[162:165]
	v_mfma_f32_16x16x32_bf16 v[162:165], v[218:221], v[12:15], v[162:165]
	v_mfma_f32_16x16x32_bf16 v[162:165], v[222:225], v[16:19], v[162:165]
	v_mfma_f32_16x16x32_bf16 v[162:165], v[226:229], v[20:23], v[162:165]
	v_mfma_f32_16x16x32_bf16 v[162:165], v[230:233], v[24:27], v[162:165]
	v_mfma_f32_16x16x32_bf16 v[162:165], v[234:237], v[28:31], v[162:165]
	s_waitcnt vmcnt(31)
	v_lshlrev_b32_e32 v170, 16, v62
	v_and_b32_e32 v171, 0xffff0000, v62
	v_mul_f32_e32 v166, 0xbfb8aa3b, v170
	v_exp_f32_e32 v166, v166
	s_nop 0
	v_add_f32_e32 v166, 1.0, v166
	v_rcp_f32_e32 v172, v166
	v_mul_f32_e32 v166, 0xbfb8aa3b, v171
	v_exp_f32_e32 v166, v166
	s_nop 0
	v_add_f32_e32 v166, 1.0, v166
	v_rcp_f32_e32 v173, v166
	s_waitcnt vmcnt(2)
	v_pk_mul_f32 v[118:119], v[118:119], v[162:163]
	v_pk_mul_f32 v[120:121], v[120:121], v[164:165]
	v_pk_mul_f32 v[172:173], v[172:173], v[170:171]
	s_nop 0
	v_pk_mul_f32 v[118:119], v[172:173], v[118:119]
	s_nop 0
	v_cvt_pk_bf16_f32 v166, v118, v119
	v_lshlrev_b32_e32 v170, 16, v63
	v_and_b32_e32 v171, 0xffff0000, v63
	v_mul_f32_e32 v167, 0xbfb8aa3b, v170
	v_exp_f32_e32 v167, v167
	s_nop 0
	v_add_f32_e32 v167, 1.0, v167
	v_rcp_f32_e32 v172, v167
	v_mul_f32_e32 v167, 0xbfb8aa3b, v171
	v_exp_f32_e32 v167, v167
	s_nop 0
	v_add_f32_e32 v167, 1.0, v167
	v_rcp_f32_e32 v173, v167
	s_nop 1
	v_pk_mul_f32 v[172:173], v[172:173], v[170:171]
	s_nop 0
	v_pk_mul_f32 v[120:121], v[172:173], v[120:121]
	s_nop 0
	v_cvt_pk_bf16_f32 v167, v120, v121
	s_nop 0
	global_store_dwordx2 v[132:133], v[166:167], off offset:2528
	s_cmp_gt_u32 s0, 1
	s_cbranch_scc1 .LBB0_554
	v_mov_b32_e32 v252, 0x3000
	s_mov_b32 s13, 0

.Lp3_ready:
	buffer_inv sc1
	s_waitcnt vmcnt(0)
	ds_read_b128 v[0:3], v160
	ds_read_b128 v[4:7], v160 offset:64
	ds_read_b128 v[8:11], v160 offset:128
	ds_read_b128 v[12:15], v160 offset:192
	ds_read_b128 v[16:19], v160 offset:256
	ds_read_b128 v[20:23], v160 offset:320
	ds_read_b128 v[24:27], v160 offset:384
	ds_read_b128 v[28:31], v160 offset:448
	ds_read_b128 v[32:35], v161
	ds_read_b128 v[36:39], v161 offset:64
	ds_read_b128 v[40:43], v161 offset:128
	ds_read_b128 v[44:47], v161 offset:192
	ds_read_b128 v[48:51], v161 offset:256
	ds_read_b128 v[52:55], v161 offset:320
	ds_read_b128 v[56:59], v161 offset:384
	ds_read_b128 v[60:63], v161 offset:448
	v_add_u32_e32 v110, v104, v141
	v_add_u32_e32 v112, v104, v142
	s_lshl_b64 s[0:1], s[8:9], 14
	v_ashrrev_i32_e32 v111, 31, v110
	v_ashrrev_i32_e32 v113, 31, v112
	v_lshl_add_u64 v[106:107], v[100:101], 0, s[0:1]
	v_lshl_add_u64 v[108:109], v[110:111], 2, s[60:61]
	v_lshl_add_u64 v[104:105], v[112:113], 2, s[60:61]
	s_and_b32 s0, s36, 63
	s_lshl_b32 s0, s0, 4
	s_mov_b64 s[8:9], 0
	v_lshlrev_b64 v[110:111], 1, v[110:111]
	v_lshlrev_b64 v[112:113], 1, v[112:113]
